# attention L0: q/k gains read from a per-wave LDS table so the item top waits only for Q (12 epilogue stores stay in flight), key step 0 skips its vmcnt(0)
# speedup vs baseline: 1.0075x; 1.0075x over previous
; #define LAS __attribute__((address_space(3)))
; __device__ __forceinline__ void attn_phase(const Params& p, LAS unsigned char* lds, int li, int tid, int G, bf16_t* __restrict__ dst, const bf16_t* __restrict__ ZGA) {
;     ...
;     auto dma_stage = [&](int item, int kb, int buf) {
;         int l = tid & 63; asm volatile("" : "+v"(l));
;         const int tb = item >> 2, hk = item & 3, tk = tb * 128 + (kb - 1) * 128;
;         LAS unsigned char* kl = lds + buf * 65536; LAS unsigned char* vl = kl + 32768;
; #pragma unroll
;         for (int i = 0; i < 4; ++i) {
;             const int r = 4 * (4 * w + i) + (l >> 4), c = (l & 15) ^ (r & 15);
;             __builtin_amdgcn_global_load_lds((const unsigned*)(ZK + (size_t)(tk + r) * 512 + hk * 128 + c * 8), (LAS unsigned*)(kl + (4 * w + i) * 1024), 16, 0, 0);
;             __builtin_amdgcn_global_load_lds((const unsigned*)(ZVT + (size_t)(hk * 128 + r) * T + tk + c * 8), (LAS unsigned*)(vl + (4 * w + i) * 1024), 16, 0, 0);
;         }
;     };
;     int buf = 0, curhk = -1;
;     int ibase, istep, icnt;
;     if (G & 7) { ibase = blockIdx.x; istep = G; icnt = ibase < 1024 ? (1024 - ibase + G - 1) / G : 0; }
;     else { const int nper = G >> 3, j0 = blockIdx.x >> 3; ibase = (blockIdx.x & 7) * 128 + j0; istep = nper; icnt = j0 < 128 ? (128 - j0 + nper - 1) / nper : 0; }
;     u32x4 qraw[3][4];
;     auto load_q = [&](int item, int lq_, int g_) {
;         const int tb = item >> 2, hk = item & 3;
; #pragma unroll
;         for (int mb = 0; mb < 3; ++mb) {
;             const int hh = mb, r = 16 * w + lq_;
;             const bf16_t* qp = Z0 + (size_t)(tb * 128 + r) * 2048 + (3 * hk + hh) * 128 + 8 * g_;
; #pragma unroll
;             for (int ks = 0; ks < 4; ++ks) qraw[mb][ks] = *(const u32x4*)(qp + 32 * ks);
;         }
;     };
;     if (icnt > 0) { dma_stage(ibase, 1, 0); load_q(ibase, tid & 15, (tid & 63) >> 4); }
.LBB0_302:
	s_ashr_i32 s1, s0, 6
	v_writelane_b32 v255, s74, 7
	s_waitcnt lgkmcnt(0)
	s_add_u32 s20, s6, 0xae00000
	s_addc_u32 s21, s7, 0
	v_writelane_b32 v255, s75, 8
	v_writelane_b32 v255, s84, 9
	s_add_u32 s22, s6, 0x12e00000
	s_load_dwordx4 s[8:11], s[4:5], 0x30
	v_writelane_b32 v255, s85, 10
	s_addc_u32 s23, s7, 0
	v_writelane_b32 v255, s86, 11
	s_add_u32 s24, s6, 0x14e00000
	v_writelane_b32 v255, s87, 12
	s_addc_u32 s25, s7, 0
	v_writelane_b32 v255, s78, 13
	s_cmp_gt_i32 s14, 0
	s_mov_b32 s27, 0
	v_writelane_b32 v255, s79, 14
	s_cselect_b64 s[4:5], -1, 0
	s_cmp_lt_i32 s14, 1
	v_and_b32_e32 v200, 63, v0
	v_writelane_b32 v255, s73, 15
	s_cbranch_scc1 .LBB0_304
	v_mov_b32_e32 v1, v200
	s_lshl_b32 s17, s15, 5
	s_waitcnt vmcnt(3)
	v_ashrrev_i32_e32 v6, 4, v1
	s_lshl_b32 s28, s1, 4
	s_and_b32 s42, s17, 0xffffff80
	v_add_u32_e32 v7, s28, v6
	v_add_u32_e32 v2, s42, v7
	s_lshl_b32 s17, s15, 7
	v_ashrrev_i32_e32 v3, 31, v2
	s_and_b32 s17, s17, 0x180
	v_xor_b32_e32 v4, v6, v1
	v_lshlrev_b64 v[2:3], 10, v[2:3]
	s_lshl_b32 s18, s1, 12
	v_lshl_add_u64 v[2:3], s[22:23], 0, v[2:3]
	s_lshl_b32 s26, s17, 1
	v_lshlrev_b32_e32 v4, 4, v4
	v_lshl_add_u64 v[2:3], v[2:3], 0, s[26:27]
	v_and_b32_e32 v4, 0xf0, v4
	v_mov_b32_e32 v5, 0
	s_add_i32 s29, s18, 0
	v_lshl_add_u64 v[2:3], v[2:3], 0, v[4:5]
	s_mov_b32 m0, s29
	s_ashr_i32 s43, s42, 31
	global_load_lds_dwordx4 v[2:3], off
	v_add_u32_e32 v2, s17, v7
	v_ashrrev_i32_e32 v3, 31, v2
	v_lshlrev_b64 v[2:3], 16, v[2:3]
	v_lshl_add_u64 v[2:3], s[24:25], 0, v[2:3]
	s_lshl_b64 s[18:19], s[42:43], 1
	s_lshl_b32 s34, s1, 2
	v_lshl_add_u64 v[2:3], v[2:3], 0, s[18:19]
	s_or_b32 s35, s34, 1
	v_lshl_add_u64 v[2:3], v[2:3], 0, v[4:5]
	s_add_i32 m0, s29, 0x8000
	v_lshl_add_u32 v7, s35, 2, v6
	global_load_lds_dwordx4 v[2:3], off
	v_add_u32_e32 v2, s42, v7
	v_ashrrev_i32_e32 v3, 31, v2
	v_xor_b32_e32 v4, v7, v1
	v_lshlrev_b64 v[2:3], 10, v[2:3]
	v_lshl_add_u64 v[2:3], s[22:23], 0, v[2:3]
	v_lshlrev_b32_e32 v4, 4, v4
	v_lshl_add_u64 v[2:3], v[2:3], 0, s[26:27]
	v_and_b32_e32 v4, 0xf0, v4
	s_lshl_b32 s35, s35, 10
	v_lshl_add_u64 v[2:3], v[2:3], 0, v[4:5]
	s_add_i32 m0, s35, 0
	s_or_b32 s35, s34, 2
	global_load_lds_dwordx4 v[2:3], off
	v_add_u32_e32 v2, s17, v7
	v_ashrrev_i32_e32 v3, 31, v2
	v_lshlrev_b64 v[2:3], 16, v[2:3]
	v_lshl_add_u64 v[2:3], s[24:25], 0, v[2:3]
	v_lshl_add_u64 v[2:3], v[2:3], 0, s[18:19]
	v_lshl_add_u64 v[2:3], v[2:3], 0, v[4:5]
	s_add_i32 m0, s29, 0x8400
	v_lshl_add_u32 v7, s35, 2, v6
	global_load_lds_dwordx4 v[2:3], off
	v_add_u32_e32 v2, s42, v7
	v_ashrrev_i32_e32 v3, 31, v2
	v_xor_b32_e32 v4, v7, v1
	v_lshlrev_b64 v[2:3], 10, v[2:3]
	v_lshl_add_u64 v[2:3], s[22:23], 0, v[2:3]
	v_lshlrev_b32_e32 v4, 4, v4
	v_lshl_add_u64 v[2:3], v[2:3], 0, s[26:27]
	v_and_b32_e32 v4, 0xf0, v4
	s_lshl_b32 s35, s35, 10
	v_lshl_add_u64 v[2:3], v[2:3], 0, v[4:5]
	s_add_i32 m0, s35, 0
	s_or_b32 s34, s34, 3
	global_load_lds_dwordx4 v[2:3], off
	v_add_u32_e32 v2, s17, v7
	v_ashrrev_i32_e32 v3, 31, v2
	v_lshlrev_b64 v[2:3], 16, v[2:3]
	v_lshl_add_u64 v[2:3], s[24:25], 0, v[2:3]
	v_lshl_add_u64 v[2:3], v[2:3], 0, s[18:19]
	v_lshl_add_u64 v[2:3], v[2:3], 0, v[4:5]
	s_add_i32 m0, s29, 0x8800
	v_lshl_add_u32 v6, s34, 2, v6
	global_load_lds_dwordx4 v[2:3], off
	v_add_u32_e32 v2, s42, v6
	v_ashrrev_i32_e32 v3, 31, v2
	v_xor_b32_e32 v1, v6, v1
	v_lshlrev_b64 v[2:3], 10, v[2:3]
	v_lshl_add_u64 v[2:3], s[22:23], 0, v[2:3]
	v_lshlrev_b32_e32 v1, 4, v1
	v_lshl_add_u64 v[2:3], v[2:3], 0, s[26:27]
	v_and_b32_e32 v4, 0xf0, v1
	s_lshl_b32 s26, s34, 10
	v_lshl_add_u64 v[2:3], v[2:3], 0, v[4:5]
	s_add_i32 m0, s26, 0
	v_bfe_u32 v1, v0, 3, 3
	v_or_b32_e32 v1, s28, v1
	global_load_lds_dwordx4 v[2:3], off
	v_add_u32_e32 v2, s17, v6
	v_ashrrev_i32_e32 v3, 31, v2
	v_lshlrev_b64 v[2:3], 16, v[2:3]
	v_lshl_add_u64 v[2:3], s[24:25], 0, v[2:3]
	v_lshl_add_u64 v[2:3], v[2:3], 0, s[18:19]
	v_lshl_add_u64 v[2:3], v[2:3], 0, v[4:5]
	s_add_i32 m0, s29, 0x8c00
	s_and_b32 s17, s15, 3
	global_load_lds_dwordx4 v[2:3], off
	v_add_u32_e32 v2, s42, v1
	v_ashrrev_i32_e32 v3, 31, v2
	v_lshlrev_b64 v[2:3], 12, v[2:3]
	v_lshl_add_u64 v[2:3], s[20:21], 0, v[2:3]
	s_mul_i32 s26, s17, 0x300
	v_lshl_add_u64 v[2:3], v[2:3], 0, s[26:27]
	v_and_b32_e32 v4, 7, v0
	v_lshlrev_b32_e32 v4, 4, v4
	v_lshl_add_u64 v[0:1], v[2:3], 0, v[4:5]
	s_mov_b32 s26, 0x8000
	v_lshl_add_u64 v[2:3], v[0:1], 0, s[26:27]
	global_load_dwordx4 v[136:139], v[0:1], off
	global_load_dwordx4 v[106:109], v[2:3], off
	global_load_dwordx4 v[102:105], v[0:1], off offset:128
	global_load_dwordx4 v[98:101], v[2:3], off offset:128
	global_load_dwordx4 v[124:127], v[0:1], off offset:256
	global_load_dwordx4 v[120:123], v[2:3], off offset:256
	global_load_dwordx4 v[116:119], v[0:1], off offset:384
	global_load_dwordx4 v[112:115], v[2:3], off offset:384
	global_load_dwordx4 v[132:135], v[0:1], off offset:512
	global_load_dwordx4 v[128:131], v[2:3], off offset:512
	global_load_dwordx4 v[144:147], v[0:1], off offset:640
	global_load_dwordx4 v[140:143], v[2:3], off offset:640
	v_mbcnt_lo_u32_b32 v10, -1, 0
	v_mbcnt_hi_u32_b32 v10, -1, v10
	v_and_b32_e32 v10, 31, v10
	v_lshlrev_b32_e32 v10, 4, v10
	s_waitcnt lgkmcnt(0)
	global_load_dwordx4 v[12:15], v10, s[8:9]
	global_load_dwordx4 v[16:19], v10, s[10:11]
	s_lshl_b32 s26, s28, 6
	s_add_i32 s26, s26, 0x25400
	v_add_u32_e32 v11, s26, v10
	s_waitcnt vmcnt(0)
	ds_write_b128 v11, v[12:15]
	ds_write_b128 v11, v[16:19] offset:512
	s_branch .LBB0_305

; __device__ __forceinline__ void attn_phase(const Params& p, LAS unsigned char* lds, int li, int tid, int G, bf16_t* __restrict__ dst, const bf16_t* __restrict__ ZGA) {
;     ...
;         bf16x8 Qf[3][4];
;         {
;             const float* qg = p.q_gain + li * 128; const float* kg = p.k_gain + li * 128;
; #pragma unroll
;             for (int mb = 0; mb < 3; ++mb) {
;                 u32x4 raw[4]; float ss = 0.f;
; #pragma unroll
;                 for (int ks = 0; ks < 4; ++ks) { raw[ks] = qraw[mb][ks];
; #pragma unroll
;                     for (int e = 0; e < 4; ++e) { const float a = bf_lo(raw[ks][e]), b = bf_hi(raw[ks][e]); ss += a * a + b * b; } }
;                 ss += __shfl_xor(ss, 16); ss += __shfl_xor(ss, 32);
;                 const float rq = rsqrtf(ss * (1.f / 128.f) + EPS) * (0.08838834764831845f * LOG2E);
; #pragma unroll
;                 for (int ks = 0; ks < 4; ++ks) {
;                     const f32x4 g0 = *(const f32x4*)(qg + 32 * ks + 8 * g) * *(const f32x4*)(kg + 32 * ks + 8 * g), g1 = *(const f32x4*)(qg + 32 * ks + 8 * g + 4) * *(const f32x4*)(kg + 32 * ks + 8 * g + 4);
.LBB0_323:
	s_waitcnt vmcnt(12)
	v_mbcnt_lo_u32_b32 v2, -1, 0
	v_mbcnt_hi_u32_b32 v2, -1, v2
	s_lshl_b32 s0, s35, 7
	s_add_i32 s0, s0, 0x21400
	v_lshrrev_b32_e32 v6, 3, v2
	v_and_b32_e32 v7, 7, v2
	v_xor_b32_e32 v7, v6, v7
	v_lshlrev_b32_e32 v7, 4, v7
	v_lshl_add_u32 v3, v6, 7, v7
	v_add_u32_e32 v3, s0, v3
	v_and_b32_e32 v6, 15, v2
	v_lshrrev_b32_e32 v7, 4, v2
	v_xor_b32_e32 v7, v7, v6
	v_and_b32_e32 v7, 3, v7
	v_lshlrev_b32_e32 v7, 4, v7
	v_lshl_add_u32 v4, v6, 7, v7
	v_bfe_u32 v7, v6, 2, 1
	v_lshl_add_u32 v4, v7, 6, v4
	v_add_u32_e32 v4, s0, v4
	v_xor_b32_e32 v5, 64, v4
	ds_write_b128 v3, v[136:139]
	ds_write_b128 v3, v[106:109] offset:1024
	ds_read_b128 v[136:139], v4
	ds_read_b128 v[106:109], v5
	ds_write_b128 v3, v[102:105]
	ds_write_b128 v3, v[98:101] offset:1024
	ds_read_b128 v[102:105], v4
	ds_read_b128 v[98:101], v5
	ds_write_b128 v3, v[124:127]
	ds_write_b128 v3, v[120:123] offset:1024
	ds_read_b128 v[124:127], v4
	ds_read_b128 v[120:123], v5
	ds_write_b128 v3, v[116:119]
	ds_write_b128 v3, v[112:115] offset:1024
	ds_read_b128 v[116:119], v4
	ds_read_b128 v[112:115], v5
	ds_write_b128 v3, v[132:135]
	ds_write_b128 v3, v[128:131] offset:1024
	ds_read_b128 v[132:135], v4
	ds_read_b128 v[128:131], v5
	ds_write_b128 v3, v[144:147]
	ds_write_b128 v3, v[140:143] offset:1024
	ds_read_b128 v[144:147], v4
	ds_read_b128 v[140:143], v5
	s_waitcnt lgkmcnt(0)
	v_and_b32_e32 v27, 0xffff0000, v136
	v_and_b32_e32 v95, 0xffff0000, v137
	v_lshlrev_b32_e32 v26, 16, v136
	v_mul_f32_e32 v6, v27, v27
	v_lshlrev_b32_e32 v94, 16, v137
	v_mul_f32_e32 v7, v95, v95
	v_fmac_f32_e32 v6, v26, v26
	v_fmac_f32_e32 v7, v94, v94
	v_and_b32_e32 v97, 0xffff0000, v138
	v_and_b32_e32 v3, 64, v202
	v_add_f32_e32 v6, v6, v7
	v_lshlrev_b32_e32 v96, 16, v138
	v_mul_f32_e32 v7, v97, v97
	v_ashrrev_i32_e32 v38, 4, v0
	v_xor_b32_e32 v2, 16, v202
	v_add_u32_e32 v39, 64, v3
	v_fmac_f32_e32 v7, v96, v96
	v_and_b32_e32 v111, 0xffff0000, v139
	v_cmp_lt_i32_e32 vcc, v2, v39
	v_lshlrev_b32_e32 v172, 3, v38
	v_add_f32_e32 v6, v7, v6
	v_lshlrev_b32_e32 v110, 16, v139
	v_mul_f32_e32 v7, v111, v111
	v_cndmask_b32_e32 v2, v202, v2, vcc
	v_ashrrev_i32_e32 v173, 31, v172
	v_fmac_f32_e32 v7, v110, v110
	v_lshlrev_b32_e32 v136, 16, v106
	v_and_b32_e32 v106, 0xffff0000, v106
	v_lshlrev_b32_e32 v204, 2, v2
	v_lshlrev_b64 v[2:3], 2, v[172:173]
	v_add_f32_e32 v6, v7, v6
	v_mul_f32_e32 v7, v106, v106
	s_waitcnt lgkmcnt(0)
	s_lshl_b32 s0, s35, 6
	s_add_i32 s0, s0, 0x25400
	v_add_u32_e32 v4, s0, v2
	v_fmac_f32_e32 v7, v136, v136
	v_add_f32_e32 v14, v7, v6
	ds_read_b128 v[6:9], v4 offset:16
	ds_read_b128 v[10:13], v4
	ds_read_b128 v[16:19], v4 offset:528
	ds_read_b128 v[20:23], v4 offset:512
	ds_read_b128 v[28:31], v4 offset:144
	ds_read_b128 v[40:43], v4 offset:128
	ds_read_b128 v[44:47], v4 offset:656
	ds_read_b128 v[48:51], v4 offset:640
	ds_read_b128 v[52:55], v4 offset:272
	ds_read_b128 v[56:59], v4 offset:256
	ds_read_b128 v[60:63], v4 offset:784
	ds_read_b128 v[64:67], v4 offset:768
	ds_read_b128 v[68:71], v4 offset:400
	ds_read_b128 v[72:75], v4 offset:384
	ds_read_b128 v[76:79], v4 offset:912
	ds_read_b128 v[80:83], v4 offset:896
	v_lshlrev_b32_e32 v137, 16, v107
	v_and_b32_e32 v107, 0xffff0000, v107
	v_mul_f32_e32 v15, v107, v107
	v_fmac_f32_e32 v15, v137, v137
	v_lshlrev_b32_e32 v138, 16, v108
	v_and_b32_e32 v108, 0xffff0000, v108
	v_add_f32_e32 v14, v15, v14
	v_mul_f32_e32 v15, v108, v108
	v_fmac_f32_e32 v15, v138, v138
	v_lshlrev_b32_e32 v139, 16, v109
	v_and_b32_e32 v109, 0xffff0000, v109
	v_add_f32_e32 v14, v15, v14
	v_mul_f32_e32 v15, v109, v109
	v_fmac_f32_e32 v15, v139, v139
	v_and_b32_e32 v85, 0xffff0000, v103
	v_and_b32_e32 v84, 0xffff0000, v102
	v_add_f32_e32 v24, v15, v14
	v_lshlrev_b32_e32 v33, 16, v103
	v_lshlrev_b32_e32 v32, 16, v102
	v_pk_mul_f32 v[14:15], v[84:85], v[84:85]
	v_and_b32_e32 v89, 0xffff0000, v105
	v_pk_fma_f32 v[14:15], v[32:33], v[32:33], v[14:15]
	v_and_b32_e32 v88, 0xffff0000, v104
	v_add_f32_e32 v14, v14, v24
	v_add_f32_e32 v24, v15, v14
	v_lshlrev_b32_e32 v87, 16, v105
	v_lshlrev_b32_e32 v86, 16, v104
	v_pk_mul_f32 v[14:15], v[88:89], v[88:89]
	v_and_b32_e32 v93, 0xffff0000, v99
	v_pk_fma_f32 v[14:15], v[86:87], v[86:87], v[14:15]
	v_and_b32_e32 v92, 0xffff0000, v98
	v_add_f32_e32 v14, v14, v24
	v_add_f32_e32 v24, v15, v14
	v_lshlrev_b32_e32 v91, 16, v99
	v_lshlrev_b32_e32 v90, 16, v98
	v_pk_mul_f32 v[14:15], v[92:93], v[92:93]
	v_and_b32_e32 v35, 0xffff0000, v101
	v_pk_fma_f32 v[14:15], v[90:91], v[90:91], v[14:15]
	v_and_b32_e32 v34, 0xffff0000, v100
	v_add_f32_e32 v14, v14, v24
	v_add_f32_e32 v24, v15, v14
	v_lshlrev_b32_e32 v37, 16, v101
	v_lshlrev_b32_e32 v36, 16, v100
	v_pk_mul_f32 v[14:15], v[34:35], v[34:35]
	s_add_i32 s95, s95, 1
	v_pk_fma_f32 v[14:15], v[36:37], v[36:37], v[14:15]
	s_add_i32 s0, s34, s2
	v_add_f32_e32 v14, v14, v24
	v_add_f32_e32 v14, v15, v14
	ds_bpermute_b32 v15, v204, v14
	v_xor_b32_e32 v24, 32, v202
	v_cmp_lt_i32_e32 vcc, v24, v39
	s_cmp_lt_i32 s95, s14
	s_cselect_b32 s97, s0, -1
	v_cndmask_b32_e32 v24, v202, v24, vcc
	v_lshlrev_b32_e32 v205, 2, v24
	s_waitcnt lgkmcnt(0)
	v_add_f32_e32 v14, v14, v15
	ds_bpermute_b32 v15, v205, v14
	s_ashr_i32 s38, s34, 2
	s_cmpk_lt_i32 s38, 0x80
	s_cselect_b32 s0, 15, 31
	s_and_b32 s1, s0, s38
	s_waitcnt lgkmcnt(0)
	v_add_f32_e32 v14, v14, v15
	v_fmamk_f32 v14, v14, 0x3c000000, v201
	v_mul_f32_e32 v15, 0x4b800000, v14
	v_cmp_gt_f32_e32 vcc, s87, v14
	s_cmp_lg_u32 s1, s0
	s_cselect_b64 s[4:5], -1, 0
	v_cndmask_b32_e32 v14, v14, v15, vcc
	v_rsq_f32_e32 v2, v14
	s_cmp_lg_u32 s1, 0
	s_cselect_b64 s[48:49], -1, 0
	s_and_b64 s[18:19], s[48:49], exec
	v_mul_f32_e32 v3, 0x45800000, v2
	v_cndmask_b32_e32 v2, v2, v3, vcc
	v_mul_f32_e32 v148, 0x3e0293ee, v2
	s_waitcnt lgkmcnt(0)
; __device__ __forceinline__ unsigned cvt_pk_bf16(float lo, float hi) { unsigned r; asm("v_cvt_pk_bf16_f32 %0, %1, %2" : "=v"(r) : "v"(lo), "v"(hi)); return r; }
; __device__ __forceinline__ void attn_phase(const Params& p, LAS unsigned char* lds, int li, int tid, int G, bf16_t* __restrict__ dst, const bf16_t* __restrict__ ZGA) {
;     ...
; #pragma unroll
;                 for (int ks = 0; ks < 4; ++ks) {
;                     const f32x4 g0 = *(const f32x4*)(qg + 32 * ks + 8 * g) * *(const f32x4*)(kg + 32 * ks + 8 * g), g1 = *(const f32x4*)(qg + 32 * ks + 8 * g + 4) * *(const f32x4*)(kg + 32 * ks + 8 * g + 4);
;                     u32x4 o;
;                     o.x = cvt_pk_bf16(bf_lo(raw[ks].x) * rq * g0[0], bf_hi(raw[ks].x) * rq * g0[1]);
;                     o.y = cvt_pk_bf16(bf_lo(raw[ks].y) * rq * g0[2], bf_hi(raw[ks].y) * rq * g0[3]);
;                     o.z = cvt_pk_bf16(bf_lo(raw[ks].z) * rq * g1[0], bf_hi(raw[ks].z) * rq * g1[1]);
;                     o.w = cvt_pk_bf16(bf_lo(raw[ks].w) * rq * g1[2], bf_hi(raw[ks].w) * rq * g1[3]);
;                     Qf[mb][ks] = __builtin_bit_cast(bf16x8, o);
;                 }
	v_pk_mul_f32 v[24:25], v[10:11], v[20:21]
	v_mul_f32_e32 v4, v148, v26
	v_mul_f32_e32 v5, v148, v27
	v_mul_f32_e32 v4, v24, v4
	v_mul_f32_e32 v5, v25, v5
	v_pk_mul_f32 v[14:15], v[12:13], v[22:23]
	v_pk_mul_f32 v[2:3], v[8:9], v[18:19]
	v_pk_mul_f32 v[8:9], v[6:7], v[16:17]
	v_cvt_pk_bf16_f32 v98, v4, v5
	v_mul_f32_e32 v4, v148, v94
	v_mul_f32_e32 v5, v148, v95
	s_waitcnt lgkmcnt(0)
	v_pk_mul_f32 v[26:27], v[40:41], v[48:49]
	v_mul_f32_e32 v6, v148, v136
	v_mul_f32_e32 v7, v148, v106
	v_mul_f32_e32 v4, v14, v4
	v_mul_f32_e32 v5, v15, v5
	v_mul_f32_e32 v6, v6, v26
	v_mul_f32_e32 v7, v7, v27
	v_cvt_pk_bf16_f32 v99, v4, v5
	v_mul_f32_e32 v4, v148, v96
	v_mul_f32_e32 v5, v148, v97
	v_pk_mul_f32 v[16:17], v[42:43], v[50:51]
	v_cvt_pk_bf16_f32 v102, v6, v7
	v_mul_f32_e32 v6, v148, v137
	v_mul_f32_e32 v7, v148, v107
	v_mul_f32_e32 v4, v8, v4
	v_mul_f32_e32 v5, v9, v5
	v_pk_mul_f32 v[10:11], v[28:29], v[44:45]
	v_mul_f32_e32 v6, v6, v16
	v_mul_f32_e32 v7, v7, v17
	s_waitcnt lgkmcnt(0)
	v_pk_mul_f32 v[28:29], v[56:57], v[64:65]
	v_mul_f32_e32 v20, v148, v32
	v_cvt_pk_bf16_f32 v100, v4, v5
	v_mul_f32_e32 v4, v148, v110
	v_mul_f32_e32 v5, v148, v111
	v_cvt_pk_bf16_f32 v103, v6, v7
	v_mul_f32_e32 v6, v148, v138
	v_mul_f32_e32 v7, v148, v108
	v_mul_f32_e32 v20, v20, v28
	v_mul_f32_e32 v21, v148, v84
	v_mul_f32_e32 v4, v2, v4
	v_mul_f32_e32 v5, v3, v5
	v_mul_f32_e32 v6, v6, v10
	v_mul_f32_e32 v7, v7, v11
	v_mul_f32_e32 v21, v21, v29
	v_cvt_pk_bf16_f32 v106, v20, v21
	v_mul_f32_e32 v20, v148, v33
	s_waitcnt lgkmcnt(0)
	v_pk_mul_f32 v[32:33], v[72:73], v[80:81]
	v_mul_f32_e32 v40, v148, v90
	v_cvt_pk_bf16_f32 v101, v4, v5
	v_pk_mul_f32 v[4:5], v[30:31], v[46:47]
	v_cvt_pk_bf16_f32 v104, v6, v7
	v_mul_f32_e32 v6, v148, v139
	v_mul_f32_e32 v7, v148, v109
	v_mul_f32_e32 v40, v40, v32
	v_mul_f32_e32 v41, v148, v92
	v_mul_f32_e32 v6, v6, v4
	v_mul_f32_e32 v7, v7, v5
	v_pk_mul_f32 v[22:23], v[74:75], v[82:83]
	v_mul_f32_e32 v41, v41, v33
	v_cvt_pk_bf16_f32 v110, v40, v41
	v_mul_f32_e32 v40, v148, v91
	v_cvt_pk_bf16_f32 v105, v6, v7
	v_pk_mul_f32 v[18:19], v[58:59], v[66:67]
	v_pk_mul_f32 v[6:7], v[54:55], v[62:63]
	v_pk_mul_f32 v[12:13], v[52:53], v[60:61]
	v_mul_f32_e32 v58, v40, v22
	v_mul_f32_e32 v40, v148, v93
	v_and_b32_e32 v61, 0xffff0000, v124
	v_and_b32_e32 v63, 0xffff0000, v125
	v_mul_f32_e32 v59, v40, v23
	v_lshlrev_b32_e32 v60, 16, v124
	v_mul_f32_e32 v40, v61, v61
	v_lshlrev_b32_e32 v62, 16, v125
	v_mul_f32_e32 v41, v63, v63
	v_mul_f32_e32 v21, v148, v85
	v_fmac_f32_e32 v40, v60, v60
	v_fmac_f32_e32 v41, v62, v62
	v_and_b32_e32 v65, 0xffff0000, v126
	v_mul_f32_e32 v20, v20, v18
	v_mul_f32_e32 v21, v21, v19
	v_add_f32_e32 v40, v40, v41
	v_lshlrev_b32_e32 v64, 16, v126
	v_mul_f32_e32 v41, v65, v65
	v_cvt_pk_bf16_f32 v107, v20, v21
	v_mul_f32_e32 v20, v148, v86
	v_mul_f32_e32 v21, v148, v88
	v_fmac_f32_e32 v41, v64, v64
	v_and_b32_e32 v67, 0xffff0000, v127
	v_mul_f32_e32 v20, v20, v12
	v_mul_f32_e32 v21, v21, v13
	v_add_f32_e32 v40, v41, v40
	v_lshlrev_b32_e32 v66, 16, v127
	v_mul_f32_e32 v41, v67, v67
	v_cvt_pk_bf16_f32 v108, v20, v21
	v_mul_f32_e32 v20, v148, v87
	v_mul_f32_e32 v21, v148, v89
	v_pk_mul_f32 v[30:31], v[68:69], v[76:77]
	v_fmac_f32_e32 v41, v66, v66
	v_and_b32_e32 v69, 0xffff0000, v120
	v_mul_f32_e32 v20, v20, v6
	v_mul_f32_e32 v21, v21, v7
	v_add_f32_e32 v40, v41, v40
	v_lshlrev_b32_e32 v68, 16, v120
	v_mul_f32_e32 v41, v69, v69
	v_cvt_pk_bf16_f32 v109, v20, v21
	v_pk_mul_f32 v[20:21], v[70:71], v[78:79]
	v_fmac_f32_e32 v41, v68, v68
	v_and_b32_e32 v71, 0xffff0000, v121
	v_add_f32_e32 v40, v41, v40
	v_lshlrev_b32_e32 v70, 16, v121
	v_mul_f32_e32 v41, v71, v71
	v_fmac_f32_e32 v41, v70, v70
	v_and_b32_e32 v73, 0xffff0000, v122
	v_add_f32_e32 v40, v41, v40
	v_lshlrev_b32_e32 v72, 16, v122
	v_mul_f32_e32 v41, v73, v73
	v_fmac_f32_e32 v41, v72, v72
	v_and_b32_e32 v75, 0xffff0000, v123
	v_add_f32_e32 v40, v41, v40
	v_lshlrev_b32_e32 v74, 16, v123
	v_mul_f32_e32 v41, v75, v75
	v_fmac_f32_e32 v41, v74, v74
	v_and_b32_e32 v43, 0xffff0000, v117
	v_and_b32_e32 v42, 0xffff0000, v116
	v_add_f32_e32 v46, v41, v40
	v_lshlrev_b32_e32 v41, 16, v117
	v_lshlrev_b32_e32 v40, 16, v116
	v_pk_mul_f32 v[44:45], v[42:43], v[42:43]
	v_and_b32_e32 v47, 0xffff0000, v119
	v_pk_fma_f32 v[44:45], v[40:41], v[40:41], v[44:45]
	v_and_b32_e32 v51, 0xffff0000, v113
	v_add_f32_e32 v44, v44, v46
	v_and_b32_e32 v46, 0xffff0000, v118
	v_add_f32_e32 v50, v45, v44
	v_lshlrev_b32_e32 v45, 16, v119
	v_lshlrev_b32_e32 v44, 16, v118
	v_pk_mul_f32 v[48:49], v[46:47], v[46:47]
	v_and_b32_e32 v55, 0xffff0000, v115
	v_pk_fma_f32 v[48:49], v[44:45], v[44:45], v[48:49]
	v_mul_f32_e32 v36, v148, v36
	v_add_f32_e32 v48, v48, v50
	v_and_b32_e32 v50, 0xffff0000, v112
	v_add_f32_e32 v54, v49, v48
	v_lshlrev_b32_e32 v49, 16, v113
	v_lshlrev_b32_e32 v48, 16, v112
	v_pk_mul_f32 v[52:53], v[50:51], v[50:51]
	v_mul_f32_e32 v36, v36, v30
	v_pk_fma_f32 v[52:53], v[48:49], v[48:49], v[52:53]
	v_mul_f32_e32 v34, v148, v34
	v_add_f32_e32 v52, v52, v54
	v_and_b32_e32 v54, 0xffff0000, v114
	v_add_f32_e32 v76, v53, v52
	v_lshlrev_b32_e32 v53, 16, v115
	v_lshlrev_b32_e32 v52, 16, v114
	v_pk_mul_f32 v[56:57], v[54:55], v[54:55]
	v_mul_f32_e32 v34, v34, v31
	v_pk_fma_f32 v[56:57], v[52:53], v[52:53], v[56:57]
	v_cvt_pk_bf16_f32 v112, v36, v34
	v_mul_f32_e32 v34, v148, v37
	v_add_f32_e32 v56, v56, v76
	v_add_f32_e32 v56, v57, v56
	ds_bpermute_b32 v57, v204, v56
	v_mul_f32_e32 v34, v34, v20
	v_mul_f32_e32 v35, v148, v35
	v_mul_f32_e32 v35, v35, v21
	v_cvt_pk_bf16_f32 v113, v34, v35
	s_waitcnt lgkmcnt(0)
; __device__ __forceinline__ unsigned cvt_pk_bf16(float lo, float hi) { unsigned r; asm("v_cvt_pk_bf16_f32 %0, %1, %2" : "=v"(r) : "v"(lo), "v"(hi)); return r; }
; __device__ __forceinline__ void attn_phase(const Params& p, LAS unsigned char* lds, int li, int tid, int G, bf16_t* __restrict__ dst, const bf16_t* __restrict__ ZGA) {
;     ...
;                 u32x4 raw[4]; float ss = 0.f;
; #pragma unroll
;                 for (int ks = 0; ks < 4; ++ks) { raw[ks] = qraw[mb][ks];
; #pragma unroll
;                     for (int e = 0; e < 4; ++e) { const float a = bf_lo(raw[ks][e]), b = bf_hi(raw[ks][e]); ss += a * a + b * b; } }
;                 ss += __shfl_xor(ss, 16); ss += __shfl_xor(ss, 32);
;                 const float rq = rsqrtf(ss * (1.f / 128.f) + EPS) * (0.08838834764831845f * LOG2E);
; #pragma unroll
;                 for (int ks = 0; ks < 4; ++ks) {
;                     const f32x4 g0 = *(const f32x4*)(qg + 32 * ks + 8 * g) * *(const f32x4*)(kg + 32 * ks + 8 * g), g1 = *(const f32x4*)(qg + 32 * ks + 8 * g + 4) * *(const f32x4*)(kg + 32 * ks + 8 * g + 4);
;                     u32x4 o;
;                     o.x = cvt_pk_bf16(bf_lo(raw[ks].x) * rq * g0[0], bf_hi(raw[ks].x) * rq * g0[1]);
;                     o.y = cvt_pk_bf16(bf_lo(raw[ks].y) * rq * g0[2], bf_hi(raw[ks].y) * rq * g0[3]);
;                     o.z = cvt_pk_bf16(bf_lo(raw[ks].z) * rq * g1[0], bf_hi(raw[ks].z) * rq * g1[1]);
;                     o.w = cvt_pk_bf16(bf_lo(raw[ks].w) * rq * g1[2], bf_hi(raw[ks].w) * rq * g1[3]);
;                     Qf[mb][ks] = __builtin_bit_cast(bf16x8, o);
;                 }
	v_add_f32_e32 v56, v56, v57
	ds_bpermute_b32 v57, v205, v56
	v_cvt_pk_bf16_f32 v111, v58, v59
	v_and_b32_e32 v76, 0xffff0000, v131
	s_cselect_b32 s1, 2, 1
	s_cmp_lg_u64 s[4:5], 0
	s_waitcnt lgkmcnt(0)
	v_add_f32_e32 v36, v56, v57
	v_fmamk_f32 v36, v36, 0x3c000000, v201
	v_mul_f32_e32 v37, 0x4b800000, v36
	v_cmp_gt_f32_e32 vcc, s87, v36
	s_addc_u32 s39, s1, 0
	s_cmp_gt_i32 s97, -1
	v_cndmask_b32_e32 v36, v36, v37, vcc
	v_rsq_f32_e32 v36, v36
	v_and_b32_e32 v37, 0xffff0000, v145
	s_cselect_b64 s[50:51], -1, 0
	s_lshl_b32 s1, s97, 5
	v_mul_f32_e32 v34, 0x45800000, v36
	v_cndmask_b32_e32 v34, v36, v34, vcc
	v_mul_f32_e32 v58, 0x3e0293ee, v34
	v_mul_f32_e32 v34, v58, v60
	v_mul_f32_e32 v34, v24, v34
	v_mul_f32_e32 v35, v58, v61
	v_mul_f32_e32 v35, v25, v35
	v_cvt_pk_bf16_f32 v114, v34, v35
	v_mul_f32_e32 v34, v58, v62
	v_mul_f32_e32 v34, v14, v34
	v_mul_f32_e32 v35, v58, v63
	v_mul_f32_e32 v35, v15, v35
	v_cvt_pk_bf16_f32 v115, v34, v35
	v_mul_f32_e32 v34, v58, v64
	v_mul_f32_e32 v34, v8, v34
	v_mul_f32_e32 v35, v58, v65
	v_mul_f32_e32 v35, v9, v35
	v_cvt_pk_bf16_f32 v116, v34, v35
	v_mul_f32_e32 v34, v58, v66
	v_mul_f32_e32 v34, v2, v34
	v_mul_f32_e32 v35, v58, v67
	v_mul_f32_e32 v35, v3, v35
	v_cvt_pk_bf16_f32 v117, v34, v35
	v_mul_f32_e32 v34, v58, v68
	v_mul_f32_e32 v34, v26, v34
	v_mul_f32_e32 v35, v58, v69
	v_mul_f32_e32 v35, v27, v35
	v_cvt_pk_bf16_f32 v118, v34, v35
	v_mul_f32_e32 v34, v58, v70
	v_mul_f32_e32 v34, v16, v34
	v_mul_f32_e32 v35, v58, v71
	v_mul_f32_e32 v35, v17, v35
	v_cvt_pk_bf16_f32 v119, v34, v35
	v_mul_f32_e32 v34, v58, v72
	v_mul_f32_e32 v34, v10, v34
	v_mul_f32_e32 v35, v58, v73
	v_mul_f32_e32 v35, v11, v35
	v_cvt_pk_bf16_f32 v120, v34, v35
	v_mul_f32_e32 v34, v58, v74
	v_mul_f32_e32 v34, v4, v34
	v_mul_f32_e32 v35, v58, v75
	v_mul_f32_e32 v35, v5, v35
	v_cvt_pk_bf16_f32 v121, v34, v35
	v_mul_f32_e32 v34, v58, v40
	v_mul_f32_e32 v34, v28, v34
	v_mul_f32_e32 v35, v58, v42
	v_mul_f32_e32 v35, v29, v35
	v_cvt_pk_bf16_f32 v122, v34, v35
	v_mul_f32_e32 v34, v58, v41
	v_mul_f32_e32 v34, v18, v34
	v_mul_f32_e32 v35, v58, v43
	v_mul_f32_e32 v35, v19, v35
	v_cvt_pk_bf16_f32 v123, v34, v35
	v_mul_f32_e32 v34, v58, v44
	v_mul_f32_e32 v34, v12, v34
	v_mul_f32_e32 v35, v58, v46
	v_mul_f32_e32 v35, v13, v35
	v_cvt_pk_bf16_f32 v124, v34, v35
	v_mul_f32_e32 v34, v58, v45
	v_mul_f32_e32 v34, v6, v34
	v_mul_f32_e32 v35, v58, v47
	v_mul_f32_e32 v35, v7, v35
	v_cvt_pk_bf16_f32 v125, v34, v35
	v_mul_f32_e32 v34, v58, v48
	v_mul_f32_e32 v34, v32, v34
	v_mul_f32_e32 v35, v58, v50
	v_mul_f32_e32 v35, v33, v35
	v_cvt_pk_bf16_f32 v126, v34, v35
	v_mul_f32_e32 v34, v58, v49
	v_mul_f32_e32 v59, v22, v34
	v_mul_f32_e32 v34, v58, v51
	v_and_b32_e32 v62, 0xffff0000, v132
	v_and_b32_e32 v64, 0xffff0000, v133
	v_mul_f32_e32 v60, v23, v34
	v_lshlrev_b32_e32 v61, 16, v132
	v_mul_f32_e32 v34, v62, v62
	v_lshlrev_b32_e32 v63, 16, v133
	v_mul_f32_e32 v35, v64, v64
	v_fmac_f32_e32 v34, v61, v61
	v_fmac_f32_e32 v35, v63, v63
	v_and_b32_e32 v66, 0xffff0000, v134
	v_add_f32_e32 v34, v34, v35
	v_lshlrev_b32_e32 v65, 16, v134
	v_mul_f32_e32 v35, v66, v66
	v_fmac_f32_e32 v35, v65, v65
	v_and_b32_e32 v68, 0xffff0000, v135
	v_add_f32_e32 v34, v35, v34
	v_lshlrev_b32_e32 v67, 16, v135
	v_mul_f32_e32 v35, v68, v68
	v_fmac_f32_e32 v35, v67, v67
	v_and_b32_e32 v70, 0xffff0000, v128
	v_add_f32_e32 v34, v35, v34
	v_lshlrev_b32_e32 v69, 16, v128
	v_mul_f32_e32 v35, v70, v70
	v_fmac_f32_e32 v35, v69, v69
	v_and_b32_e32 v72, 0xffff0000, v129
	v_add_f32_e32 v34, v35, v34
	v_lshlrev_b32_e32 v71, 16, v129
	v_mul_f32_e32 v35, v72, v72
	v_fmac_f32_e32 v35, v71, v71
	v_and_b32_e32 v74, 0xffff0000, v130
	v_add_f32_e32 v34, v35, v34
	v_lshlrev_b32_e32 v73, 16, v130
	v_mul_f32_e32 v35, v74, v74
	v_fmac_f32_e32 v35, v73, v73
	v_add_f32_e32 v34, v35, v34
	v_lshlrev_b32_e32 v75, 16, v131
	v_mul_f32_e32 v35, v76, v76
	v_fmac_f32_e32 v35, v75, v75
	v_and_b32_e32 v36, 0xffff0000, v144
	v_add_f32_e32 v42, v35, v34
	v_lshlrev_b32_e32 v35, 16, v145
	v_lshlrev_b32_e32 v34, 16, v144
	v_pk_mul_f32 v[40:41], v[36:37], v[36:37]
	v_and_b32_e32 v43, 0xffff0000, v147
	v_pk_fma_f32 v[40:41], v[34:35], v[34:35], v[40:41]
	v_and_b32_e32 v47, 0xffff0000, v141
	v_add_f32_e32 v40, v40, v42
	v_and_b32_e32 v42, 0xffff0000, v146
	v_add_f32_e32 v46, v41, v40
	v_lshlrev_b32_e32 v41, 16, v147
	v_lshlrev_b32_e32 v40, 16, v146
	v_pk_mul_f32 v[44:45], v[42:43], v[42:43]
	v_and_b32_e32 v51, 0xffff0000, v143
	v_pk_fma_f32 v[44:45], v[40:41], v[40:41], v[44:45]
	v_mul_f32_e32 v52, v58, v52
	v_add_f32_e32 v44, v44, v46
	v_and_b32_e32 v46, 0xffff0000, v140
	v_add_f32_e32 v50, v45, v44
	v_lshlrev_b32_e32 v45, 16, v141
	v_lshlrev_b32_e32 v44, 16, v140
	v_pk_mul_f32 v[48:49], v[46:47], v[46:47]
	v_mul_f32_e32 v52, v30, v52
	v_pk_fma_f32 v[48:49], v[44:45], v[44:45], v[48:49]
	v_mul_f32_e32 v54, v58, v54
	v_add_f32_e32 v48, v48, v50
	v_and_b32_e32 v50, 0xffff0000, v142
	v_add_f32_e32 v77, v49, v48
	v_lshlrev_b32_e32 v49, 16, v143
	v_lshlrev_b32_e32 v48, 16, v142
	v_pk_mul_f32 v[56:57], v[50:51], v[50:51]
	v_mul_f32_e32 v54, v31, v54
	v_pk_fma_f32 v[56:57], v[48:49], v[48:49], v[56:57]
	v_cvt_pk_bf16_f32 v128, v52, v54
	v_mul_f32_e32 v52, v58, v53
	v_add_f32_e32 v56, v56, v77
	v_add_f32_e32 v56, v57, v56
	ds_bpermute_b32 v57, v204, v56
	v_mul_f32_e32 v52, v20, v52
	s_and_b32 s41, s1, 0x7fffff80
	s_lshl_b32 s1, s97, 7
	s_and_b32 s28, s1, 0x180
	s_waitcnt lgkmcnt(0)
	v_add_f32_e32 v56, v56, v57
	ds_bpermute_b32 v57, v205, v56
	s_lshl_b32 s1, s28, 1
	s_add_u32 s52, s22, s1
	s_addc_u32 s53, s23, 0
	s_lshl_b32 s1, s41, 1
	s_waitcnt lgkmcnt(0)
; #define LAS __attribute__((address_space(3)))
; __device__ __forceinline__ unsigned cvt_pk_bf16(float lo, float hi) { unsigned r; asm("v_cvt_pk_bf16_f32 %0, %1, %2" : "=v"(r) : "v"(lo), "v"(hi)); return r; }
; __device__ __forceinline__ void attn_phase(const Params& p, LAS unsigned char* lds, int li, int tid, int G, bf16_t* __restrict__ dst, const bf16_t* __restrict__ ZGA) {
;     ...
;                 const float rq = rsqrtf(ss * (1.f / 128.f) + EPS) * (0.08838834764831845f * LOG2E);
; #pragma unroll
;                 for (int ks = 0; ks < 4; ++ks) {
;                     const f32x4 g0 = *(const f32x4*)(qg + 32 * ks + 8 * g) * *(const f32x4*)(kg + 32 * ks + 8 * g), g1 = *(const f32x4*)(qg + 32 * ks + 8 * g + 4) * *(const f32x4*)(kg + 32 * ks + 8 * g + 4);
;                     u32x4 o;
;                     o.x = cvt_pk_bf16(bf_lo(raw[ks].x) * rq * g0[0], bf_hi(raw[ks].x) * rq * g0[1]);
;                     o.y = cvt_pk_bf16(bf_lo(raw[ks].y) * rq * g0[2], bf_hi(raw[ks].y) * rq * g0[3]);
;                     o.z = cvt_pk_bf16(bf_lo(raw[ks].z) * rq * g1[0], bf_hi(raw[ks].z) * rq * g1[1]);
;                     o.w = cvt_pk_bf16(bf_lo(raw[ks].w) * rq * g1[2], bf_hi(raw[ks].w) * rq * g1[3]);
;                     Qf[mb][ks] = __builtin_bit_cast(bf16x8, o);
;                 }
;             }
;         }
;         f32x4 oacc[3][8];
;         float lrun[3];
; #pragma unroll
;         for (int mb = 0; mb < 3; ++mb) {
;             lrun[mb] = 0.f;
; #pragma unroll
;             for (int db = 0; db < 8; ++db) oacc[mb][db] = (f32x4){0.f, 0.f, 0.f, 0.f};
;         }
; #pragma unroll 1
;         for (int step = 0; step < nkb; ++step) {
;             const int kb = (step == 0) ? 1 : ((step == 1 && has0) ? 0 : 2);
;             asm volatile("s_waitcnt vmcnt(0)" ::: "memory");
;             LAS unsigned char* KS = lds + buf * 65536; LAS unsigned char* VS = KS + 32768;
;             {
;                 const int key = 16 * w + (l >> 2), part = l & 3;
	v_add_f32_e32 v53, v56, v57
	v_fmamk_f32 v53, v53, 0x3c000000, v201
	v_mul_f32_e32 v54, 0x4b800000, v53
	v_cmp_gt_f32_e32 vcc, s87, v53
	s_add_u32 s54, s24, s1
	v_and_b32_e32 v208, 15, v0
	v_cndmask_b32_e32 v53, v53, v54, vcc
	v_rsq_f32_e32 v53, v53
	v_mul_f32_e32 v54, v58, v55
	v_mul_f32_e32 v54, v21, v54
	v_cvt_pk_bf16_f32 v129, v52, v54
	v_mul_f32_e32 v52, 0x45800000, v53
	v_cndmask_b32_e32 v52, v53, v52, vcc
	v_mul_f32_e32 v52, 0x3e0293ee, v52
	v_mul_f32_e32 v53, v52, v61
	v_mul_f32_e32 v24, v24, v53
	v_mul_f32_e32 v53, v52, v62
	v_mul_f32_e32 v25, v25, v53
	v_cvt_pk_bf16_f32 v130, v24, v25
	v_mul_f32_e32 v24, v52, v63
	v_mul_f32_e32 v14, v14, v24
	v_mul_f32_e32 v24, v52, v64
	v_mul_f32_e32 v15, v15, v24
	v_cvt_pk_bf16_f32 v131, v14, v15
	v_mul_f32_e32 v14, v52, v65
	v_mul_f32_e32 v8, v8, v14
	v_mul_f32_e32 v14, v52, v66
	v_mul_f32_e32 v9, v9, v14
	v_cvt_pk_bf16_f32 v132, v8, v9
	v_mul_f32_e32 v8, v52, v67
	v_mul_f32_e32 v2, v2, v8
	v_mul_f32_e32 v8, v52, v68
	v_mul_f32_e32 v3, v3, v8
	v_cvt_pk_bf16_f32 v133, v2, v3
	v_mul_f32_e32 v2, v52, v69
	v_mul_f32_e32 v2, v26, v2
	v_mul_f32_e32 v3, v52, v70
	v_mul_f32_e32 v3, v27, v3
	v_cvt_pk_bf16_f32 v134, v2, v3
	v_mul_f32_e32 v2, v52, v71
	v_mul_f32_e32 v2, v16, v2
	v_mul_f32_e32 v3, v52, v72
	v_mul_f32_e32 v3, v17, v3
	v_cvt_pk_bf16_f32 v135, v2, v3
	v_mul_f32_e32 v2, v52, v73
	v_mul_f32_e32 v2, v10, v2
	v_mul_f32_e32 v3, v52, v74
	v_mul_f32_e32 v3, v11, v3
	v_cvt_pk_bf16_f32 v136, v2, v3
	v_mul_f32_e32 v2, v52, v75
	v_mul_f32_e32 v2, v4, v2
	v_mul_f32_e32 v3, v52, v76
	v_mul_f32_e32 v3, v5, v3
	v_cvt_pk_bf16_f32 v137, v2, v3
	v_mul_f32_e32 v2, v52, v34
	v_mul_f32_e32 v2, v28, v2
	v_mul_f32_e32 v3, v52, v36
	v_mul_f32_e32 v3, v29, v3
	v_cvt_pk_bf16_f32 v138, v2, v3
	v_mul_f32_e32 v2, v52, v35
	v_mul_f32_e32 v2, v18, v2
	v_mul_f32_e32 v3, v52, v37
	v_mul_f32_e32 v3, v19, v3
	v_cvt_pk_bf16_f32 v139, v2, v3
	v_mul_f32_e32 v2, v52, v40
	v_mul_f32_e32 v2, v12, v2
	v_mul_f32_e32 v3, v52, v42
	v_mul_f32_e32 v3, v13, v3
	v_cvt_pk_bf16_f32 v140, v2, v3
	v_mul_f32_e32 v2, v52, v41
	v_mul_f32_e32 v2, v6, v2
	v_mul_f32_e32 v3, v52, v43
	v_mul_f32_e32 v3, v7, v3
	v_cvt_pk_bf16_f32 v141, v2, v3
	v_mul_f32_e32 v2, v52, v44
	v_mul_f32_e32 v2, v32, v2
	v_mul_f32_e32 v3, v52, v46
	v_mul_f32_e32 v3, v33, v3
	v_cvt_pk_bf16_f32 v142, v2, v3
	v_mul_f32_e32 v2, v52, v45
	v_mul_f32_e32 v2, v22, v2
	v_mul_f32_e32 v3, v52, v47
	v_mul_f32_e32 v3, v23, v3
	v_cvt_pk_bf16_f32 v143, v2, v3
	v_mul_f32_e32 v2, v52, v48
	v_mul_f32_e32 v2, v30, v2
	v_mul_f32_e32 v3, v52, v50
	v_mul_f32_e32 v3, v31, v3
	v_cvt_pk_bf16_f32 v144, v2, v3
	v_mul_f32_e32 v2, v52, v49
	v_mul_f32_e32 v2, v20, v2
	v_mul_f32_e32 v3, v52, v51
	v_mul_f32_e32 v3, v21, v3
	v_cvt_pk_bf16_f32 v145, v2, v3
	v_ashrrev_i32_e32 v2, 2, v0
	v_add_lshl_u32 v171, v2, s35, 8
	v_lshlrev_b32_e32 v3, 2, v0
	v_and_b32_e32 v2, 15, v2
	v_and_b32_e32 v4, 12, v3
	v_bitop3_b32 v3, v3, v2, 12 bitop3:0x6c
	v_lshlrev_b32_e32 v177, 4, v3
	v_bitop3_b32 v3, v4, v2, 1 bitop3:0x36
	v_lshlrev_b32_e32 v178, 4, v3
	v_bitop3_b32 v3, v4, v2, 2 bitop3:0x36
	v_bitop3_b32 v2, v4, v2, 3 bitop3:0x36
	v_lshlrev_b32_e32 v180, 4, v2
	v_xor_b32_e32 v2, 1, v202
	v_cmp_lt_i32_e32 vcc, v2, v39
	s_addc_u32 s55, s25, 0
	s_lshl_b32 s1, s34, 5
	v_cndmask_b32_e32 v2, v202, v2, vcc
	v_lshlrev_b32_e32 v181, 2, v2
	v_xor_b32_e32 v2, 2, v202
	v_cmp_lt_i32_e32 vcc, v2, v39
	v_lshlrev_b32_e32 v179, 4, v3
	v_add_u32_e32 v3, 4, v38
	v_cndmask_b32_e32 v2, v202, v2, vcc
	s_and_b32 s29, s1, 0xffffff80
	s_lshl_b32 s1, s34, 7
	v_lshlrev_b32_e32 v174, 8, v208
	v_lshlrev_b32_e32 v182, 2, v2
	v_bitop3_b32 v2, v38, v0, 15 bitop3:0x78
	v_bitop3_b32 v3, v3, v0, 15 bitop3:0x78
	v_add_u32_e32 v4, 8, v38
	v_add_u32_e32 v5, 12, v38
	s_and_b32 s1, s1, 0x180
	v_lshlrev_b32_e32 v170, 2, v38
	v_ashrrev_i32_e32 v176, 5, v0
	v_bitop3_b32 v4, v4, v0, 15 bitop3:0x78
	v_bitop3_b32 v0, v5, v0, 15 bitop3:0x78
	v_lshl_add_u32 v184, v2, 4, v174
	v_lshl_add_u32 v185, v3, 4, v174
	v_mov_b32_e32 v2, v1
	v_mov_b32_e32 v3, v1
	v_cvt_pk_bf16_f32 v127, v59, v60
	s_lshl_b32 s4, s1, 1
	v_add_u32_e32 v5, s85, v170
	v_lshl_add_u32 v187, v0, 4, v174
	v_mov_b32_e32 v0, v1
	v_mov_b64_e32 v[80:81], v[2:3]
	v_mov_b64_e32 v[84:85], v[2:3]
	v_mov_b64_e32 v[88:89], v[2:3]
	v_mov_b64_e32 v[92:93], v[2:3]
	v_mov_b64_e32 v[96:97], v[2:3]
	v_mov_b64_e32 v[76:77], v[2:3]
	v_mov_b64_e32 v[72:73], v[2:3]
	v_mov_b64_e32 v[68:69], v[2:3]
	v_mov_b64_e32 v[64:65], v[2:3]
	v_mov_b64_e32 v[60:61], v[2:3]
	v_mov_b64_e32 v[56:57], v[2:3]
	v_mov_b64_e32 v[52:53], v[2:3]
	v_mov_b64_e32 v[48:49], v[2:3]
	v_mov_b64_e32 v[44:45], v[2:3]
	v_mov_b64_e32 v[40:41], v[2:3]
	v_mov_b64_e32 v[36:37], v[2:3]
	v_mov_b64_e32 v[32:33], v[2:3]
	v_mov_b64_e32 v[28:29], v[2:3]
	v_mov_b64_e32 v[24:25], v[2:3]
	v_mov_b64_e32 v[20:21], v[2:3]
	v_mov_b64_e32 v[16:17], v[2:3]
	v_mov_b64_e32 v[12:13], v[2:3]
	v_mov_b64_e32 v[8:9], v[2:3]
	s_add_u32 s56, s22, s4
	v_sub_u32_e32 v183, v5, v208
	v_lshl_add_u32 v186, v4, 4, v174
	v_mov_b64_e32 v[78:79], v[0:1]
	v_mov_b64_e32 v[82:83], v[0:1]
	v_mov_b64_e32 v[86:87], v[0:1]
	v_mov_b64_e32 v[90:91], v[0:1]
	v_mov_b64_e32 v[94:95], v[0:1]
	v_mov_b64_e32 v[74:75], v[0:1]
	v_mov_b64_e32 v[70:71], v[0:1]
	v_mov_b64_e32 v[66:67], v[0:1]
	v_mov_b64_e32 v[62:63], v[0:1]
	v_mov_b64_e32 v[58:59], v[0:1]
	v_mov_b64_e32 v[54:55], v[0:1]
	v_mov_b64_e32 v[50:51], v[0:1]
	v_mov_b64_e32 v[46:47], v[0:1]
	v_mov_b64_e32 v[42:43], v[0:1]
	v_mov_b64_e32 v[38:39], v[0:1]
	v_mov_b64_e32 v[34:35], v[0:1]
	v_mov_b64_e32 v[30:31], v[0:1]
	v_mov_b64_e32 v[26:27], v[0:1]
	v_mov_b64_e32 v[22:23], v[0:1]
	v_mov_b64_e32 v[18:19], v[0:1]
	v_mov_b64_e32 v[14:15], v[0:1]
	v_mov_b64_e32 v[10:11], v[0:1]
	v_mov_b64_e32 v[6:7], v[0:1]
	v_mov_b64_e32 v[4:5], v[2:3]
	s_mov_b32 s0, 0
	s_addc_u32 s57, s23, 0
	v_and_b32_e32 v175, 8, v172
	v_mov_b32_e32 v206, 0
	v_mov_b32_e32 v207, 0
	v_mov_b32_e32 v209, 0
	v_mov_b64_e32 v[2:3], v[0:1]
; #define LAS __attribute__((address_space(3)))
; __device__ __forceinline__ unsigned cvt_pk_bf16(float lo, float hi) { unsigned r; asm("v_cvt_pk_bf16_f32 %0, %1, %2" : "=v"(r) : "v"(lo), "v"(hi)); return r; }
; __device__ __forceinline__ void attn_phase(const Params& p, LAS unsigned char* lds, int li, int tid, int G, bf16_t* __restrict__ dst, const bf16_t* __restrict__ ZGA) {
;     ...
;         for (int step = 0; step < nkb; ++step) {
;             const int kb = (step == 0) ? 1 : ((step == 1 && has0) ? 0 : 2);
;             asm volatile("s_waitcnt vmcnt(0)" ::: "memory");
;             LAS unsigned char* KS = lds + buf * 65536; LAS unsigned char* VS = KS + 32768;
;             {
;                 const int key = 16 * w + (l >> 2), part = l & 3;
;                 u32x4 v[4]; float ss = 0.f;
; #pragma unroll
;                 for (int i = 0; i < 4; ++i) { v[i] = *(const LAS u32x4*)(KS + key * 256 + (((4 * part + i) ^ (key & 15)) << 4));
; #pragma unroll
;                     for (int e = 0; e < 4; ++e) { const float a = bf_lo(v[i][e]), b = bf_hi(v[i][e]); ss += a * a + b * b; } }
;                 ss += __shfl_xor(ss, 1); ss += __shfl_xor(ss, 2);
;                 const float rk = rsqrtf(ss * (1.f / 128.f) + EPS);
; #pragma unroll
;                 for (int i = 0; i < 4; ++i) { u32x4 o;
; #pragma unroll
;                     for (int e = 0; e < 4; ++e) o[e] = cvt_pk_bf16(bf_lo(v[i][e]) * rk, bf_hi(v[i][e]) * rk);
;                     *(LAS u32x4*)(KS + key * 256 + (((4 * part + i) ^ (key & 15)) << 4)) = o; }
;             }
;             __syncthreads();
.LBB0_324:
	s_lshl_b32 s19, s94, 16
	s_add_i32 s64, s19, 0
	v_add_u32_e32 v0, s64, v171
	s_cmp_eq_u32 s0, 0
	s_cbranch_scc1 .Lattn0_nowait
	s_waitcnt vmcnt(0)
.Lattn0_nowait:
	v_add_u32_e32 v166, v0, v177
	ds_read_b128 v[146:149], v166
	v_add_u32_e32 v167, v0, v178
	ds_read_b128 v[150:153], v167
	v_add_u32_e32 v212, v0, v179
	v_add_u32_e32 v0, v0, v180
	s_waitcnt lgkmcnt(0)
	v_and_b32_e32 v169, 0xffff0000, v146
	v_and_b32_e32 v189, 0xffff0000, v147
	v_lshlrev_b32_e32 v168, 16, v146
	v_mul_f32_e32 v146, v169, v169
	v_lshlrev_b32_e32 v188, 16, v147
	v_mul_f32_e32 v147, v189, v189
	v_fmac_f32_e32 v146, v168, v168
	v_fmac_f32_e32 v147, v188, v188
	v_and_b32_e32 v191, 0xffff0000, v148
	v_add_f32_e32 v146, v146, v147
	v_lshlrev_b32_e32 v190, 16, v148
	v_mul_f32_e32 v147, v191, v191
	v_fmac_f32_e32 v147, v190, v190
	v_and_b32_e32 v193, 0xffff0000, v149
	v_add_f32_e32 v146, v147, v146
	v_lshlrev_b32_e32 v192, 16, v149
	v_mul_f32_e32 v147, v193, v193
	v_fmac_f32_e32 v147, v192, v192
	s_waitcnt lgkmcnt(0)
	v_and_b32_e32 v195, 0xffff0000, v150
	v_add_f32_e32 v146, v147, v146
	v_lshlrev_b32_e32 v194, 16, v150
	v_mul_f32_e32 v147, v195, v195
	v_fmac_f32_e32 v147, v194, v194
	v_and_b32_e32 v197, 0xffff0000, v151
	v_add_f32_e32 v146, v147, v146
	v_lshlrev_b32_e32 v196, 16, v151
	v_mul_f32_e32 v147, v197, v197
	v_fmac_f32_e32 v147, v196, v196
	v_and_b32_e32 v199, 0xffff0000, v152
	v_add_f32_e32 v146, v147, v146
	v_lshlrev_b32_e32 v198, 16, v152
	v_mul_f32_e32 v147, v199, v199
	v_fmac_f32_e32 v147, v198, v198
	v_add_f32_e32 v150, v147, v146
	ds_read_b128 v[146:149], v212
	v_and_b32_e32 v211, 0xffff0000, v153
	v_lshlrev_b32_e32 v210, 16, v153
	v_mul_f32_e32 v151, v211, v211
	v_fmac_f32_e32 v151, v210, v210
	v_add_f32_e32 v158, v151, v150
	ds_read_b128 v[150:153], v0
	s_waitcnt lgkmcnt(0)
	v_and_b32_e32 v157, 0xffff0000, v147
	v_and_b32_e32 v156, 0xffff0000, v146
	v_lshlrev_b32_e32 v155, 16, v147
	v_lshlrev_b32_e32 v154, 16, v146
	v_pk_mul_f32 v[146:147], v[156:157], v[156:157]
	v_and_b32_e32 v161, 0xffff0000, v149
	v_pk_fma_f32 v[146:147], v[154:155], v[154:155], v[146:147]
	v_and_b32_e32 v160, 0xffff0000, v148
	v_add_f32_e32 v146, v146, v158
	v_add_f32_e32 v162, v147, v146
	v_lshlrev_b32_e32 v159, 16, v149
	v_lshlrev_b32_e32 v158, 16, v148
	v_pk_mul_f32 v[146:147], v[160:161], v[160:161]
	s_waitcnt lgkmcnt(0)
	v_lshlrev_b32_e32 v163, 16, v151
	v_pk_fma_f32 v[146:147], v[158:159], v[158:159], v[146:147]
	v_and_b32_e32 v151, 0xffff0000, v151
	v_add_f32_e32 v146, v146, v162
	v_lshlrev_b32_e32 v162, 16, v150
	v_and_b32_e32 v150, 0xffff0000, v150
	v_add_f32_e32 v148, v147, v146
	v_pk_mul_f32 v[146:147], v[150:151], v[150:151]
	v_lshlrev_b32_e32 v165, 16, v153
	v_pk_fma_f32 v[146:147], v[162:163], v[162:163], v[146:147]
	v_lshlrev_b32_e32 v164, 16, v152
	v_add_f32_e32 v146, v146, v148
	v_and_b32_e32 v153, 0xffff0000, v153
	v_and_b32_e32 v152, 0xffff0000, v152
	v_add_f32_e32 v148, v147, v146
	v_pk_mul_f32 v[146:147], v[152:153], v[152:153]
	s_cmp_eq_u32 s0, 0
	v_pk_fma_f32 v[146:147], v[164:165], v[164:165], v[146:147]
	s_cselect_b64 s[58:59], -1, 0
	v_add_f32_e32 v146, v146, v148
	v_add_f32_e32 v146, v147, v146
	ds_bpermute_b32 v147, v181, v146
	s_cmp_lg_u32 s0, 0
	s_cselect_b64 s[60:61], -1, 0
	s_add_i32 s81, s0, 1
	s_cmp_ge_u32 s81, s39
	s_waitcnt lgkmcnt(0)
	v_add_f32_e32 v146, v146, v147
	ds_bpermute_b32 v147, v182, v146
	s_waitcnt lgkmcnt(0)
	v_add_f32_e32 v146, v146, v147
	v_fmamk_f32 v146, v146, 0x3c000000, v201
	v_mul_f32_e32 v147, 0x4b800000, v146
	v_cmp_gt_f32_e32 vcc, s87, v146
	s_nop 1
	v_cndmask_b32_e32 v146, v146, v147, vcc
	v_rsq_f32_e32 v146, v146
	s_nop 0
	v_mul_f32_e32 v147, 0x45800000, v146
	v_cndmask_b32_e32 v213, v146, v147, vcc
	v_mul_f32_e32 v146, v213, v168
	v_mul_f32_e32 v147, v213, v169
	v_cvt_pk_bf16_f32 v146, v146, v147
	v_mul_f32_e32 v147, v213, v188
	v_mul_f32_e32 v148, v213, v189
	v_cvt_pk_bf16_f32 v147, v147, v148
	v_mul_f32_e32 v148, v213, v190
	v_mul_f32_e32 v149, v213, v191
	v_cvt_pk_bf16_f32 v148, v148, v149
	v_mul_f32_e32 v149, v213, v192
	v_mul_f32_e32 v168, v213, v193
	v_cvt_pk_bf16_f32 v149, v149, v168
	ds_write_b128 v166, v[146:149]
	v_mul_f32_e32 v146, v213, v194
	v_mul_f32_e32 v147, v213, v195
	v_cvt_pk_bf16_f32 v146, v146, v147
	v_mul_f32_e32 v147, v213, v196
	v_mul_f32_e32 v148, v213, v197
	v_cvt_pk_bf16_f32 v147, v147, v148
	v_mul_f32_e32 v148, v213, v198
	v_mul_f32_e32 v149, v213, v199
	v_cvt_pk_bf16_f32 v148, v148, v149
	v_mul_f32_e32 v149, v213, v210
	v_mul_f32_e32 v166, v213, v211
	v_cvt_pk_bf16_f32 v149, v149, v166
	ds_write_b128 v167, v[146:149]
	v_mul_f32_e32 v146, v213, v154
	v_mul_f32_e32 v147, v213, v156
	v_cvt_pk_bf16_f32 v146, v146, v147
	v_mul_f32_e32 v147, v213, v155
	v_mul_f32_e32 v148, v213, v157
	v_cvt_pk_bf16_f32 v147, v147, v148
	v_mul_f32_e32 v148, v213, v158
	v_mul_f32_e32 v149, v213, v160
	v_cvt_pk_bf16_f32 v148, v148, v149
	v_mul_f32_e32 v149, v213, v159
	v_mul_f32_e32 v154, v213, v161
	v_cvt_pk_bf16_f32 v149, v149, v154
	ds_write_b128 v212, v[146:149]
	v_mul_f32_e32 v146, v213, v162
	v_mul_f32_e32 v147, v213, v150
	v_cvt_pk_bf16_f32 v146, v146, v147
	v_mul_f32_e32 v147, v213, v163
	v_mul_f32_e32 v148, v213, v151
	v_cvt_pk_bf16_f32 v147, v147, v148
	v_mul_f32_e32 v148, v213, v164
	v_mul_f32_e32 v149, v213, v152
	v_cvt_pk_bf16_f32 v148, v148, v149
	v_mul_f32_e32 v149, v213, v165
	v_mul_f32_e32 v150, v213, v153
	v_cvt_pk_bf16_f32 v149, v149, v150
	ds_write_b128 v0, v[146:149]
	s_waitcnt lgkmcnt(0)
	s_barrier
; #define LAS __attribute__((address_space(3)))
; __device__ __forceinline__ void attn_phase(const Params& p, LAS unsigned char* lds, int li, int tid, int G, bf16_t* __restrict__ dst, const bf16_t* __restrict__ ZGA) {
;     ...
;     auto dma_stage = [&](int item, int kb, int buf) {
;         int l = tid & 63; asm volatile("" : "+v"(l));
;         const int tb = item >> 2, hk = item & 3, tk = tb * 128 + (kb - 1) * 128;
;         LAS unsigned char* kl = lds + buf * 65536; LAS unsigned char* vl = kl + 32768;
; #pragma unroll
;         for (int i = 0; i < 4; ++i) {
;             const int r = 4 * (4 * w + i) + (l >> 4), c = (l & 15) ^ (r & 15);
;             __builtin_amdgcn_global_load_lds((const unsigned*)(ZK + (size_t)(tk + r) * 512 + hk * 128 + c * 8), (LAS unsigned*)(kl + (4 * w + i) * 1024), 16, 0, 0);
;             __builtin_amdgcn_global_load_lds((const unsigned*)(ZVT + (size_t)(hk * 128 + r) * T + tk + c * 8), (LAS unsigned*)(vl + (4 * w + i) * 1024), 16, 0, 0);
;         }
	s_cbranch_scc0 .LBB0_366
	s_mov_b64 s[4:5], 0
	s_and_b64 vcc, exec, s[50:51]
	s_mov_b64 s[62:63], 0
	s_cbranch_vccz .LBB0_327
	v_mov_b32_e32 v148, v200
	s_xor_b32 s18, s19, 0x10000
	v_ashrrev_i32_e32 v149, 4, v148
	v_add_u32_e32 v150, s35, v149
	v_add_u32_e32 v146, s41, v150
	v_xor_b32_e32 v0, v149, v148
	v_ashrrev_i32_e32 v147, 31, v146
	s_add_i32 s62, s18, 0
	v_lshlrev_b64 v[146:147], 10, v[146:147]
	v_lshlrev_b32_e32 v0, 4, v0
	v_lshl_add_u64 v[146:147], s[52:53], 0, v[146:147]
	v_and_b32_e32 v0, 0xf0, v0
	s_add_i32 s63, s62, s70
	v_lshl_add_u64 v[146:147], v[146:147], 0, v[0:1]
	s_mov_b32 m0, s63
	s_nop 0
	global_load_lds_dwordx4 v[146:147], off
	v_add_u32_e32 v146, s28, v150
	v_ashrrev_i32_e32 v147, 31, v146
	v_lshlrev_b64 v[146:147], 16, v[146:147]
	v_lshl_add_u64 v[146:147], s[54:55], 0, v[146:147]
	v_lshl_add_u64 v[146:147], v[146:147], 0, v[0:1]
	s_add_i32 m0, s63, 0x8000
	v_add_u32_e32 v150, s71, v149
	global_load_lds_dwordx4 v[146:147], off
	v_add_u32_e32 v146, s41, v150
	v_xor_b32_e32 v0, v150, v148
	v_ashrrev_i32_e32 v147, 31, v146
	v_lshlrev_b64 v[146:147], 10, v[146:147]
	v_lshlrev_b32_e32 v0, 4, v0
	v_lshl_add_u64 v[146:147], s[52:53], 0, v[146:147]
	v_and_b32_e32 v0, 0xf0, v0
	v_lshl_add_u64 v[146:147], v[146:147], 0, v[0:1]
	s_add_i32 m0, s62, s72
	s_nop 0
	global_load_lds_dwordx4 v[146:147], off
	v_add_u32_e32 v146, s28, v150
	v_ashrrev_i32_e32 v147, 31, v146
	v_lshlrev_b64 v[146:147], 16, v[146:147]
	v_lshl_add_u64 v[146:147], s[54:55], 0, v[146:147]
	v_lshl_add_u64 v[146:147], v[146:147], 0, v[0:1]
	s_add_i32 m0, s63, 0x8400
	v_add_u32_e32 v150, s73, v149
	global_load_lds_dwordx4 v[146:147], off
	v_add_u32_e32 v146, s41, v150
	v_xor_b32_e32 v0, v150, v148
	v_ashrrev_i32_e32 v147, 31, v146
	v_lshlrev_b64 v[146:147], 10, v[146:147]
	v_lshlrev_b32_e32 v0, 4, v0
	v_lshl_add_u64 v[146:147], s[52:53], 0, v[146:147]
	v_and_b32_e32 v0, 0xf0, v0
	v_lshl_add_u64 v[146:147], v[146:147], 0, v[0:1]
	s_add_i32 m0, s62, s74
	v_add_u32_e32 v149, s75, v149
	global_load_lds_dwordx4 v[146:147], off
	v_add_u32_e32 v146, s28, v150
	v_ashrrev_i32_e32 v147, 31, v146
	v_lshlrev_b64 v[146:147], 16, v[146:147]
	v_lshl_add_u64 v[146:147], s[54:55], 0, v[146:147]
	v_lshl_add_u64 v[146:147], v[146:147], 0, v[0:1]
	s_add_i32 m0, s63, 0x8800
	v_xor_b32_e32 v0, v149, v148
	global_load_lds_dwordx4 v[146:147], off
	v_add_u32_e32 v146, s41, v149
	v_ashrrev_i32_e32 v147, 31, v146
	v_lshlrev_b64 v[146:147], 10, v[146:147]
	v_lshlrev_b32_e32 v0, 4, v0
	v_lshl_add_u64 v[146:147], s[52:53], 0, v[146:147]
	v_and_b32_e32 v0, 0xf0, v0
	v_lshl_add_u64 v[146:147], v[146:147], 0, v[0:1]
	s_add_i32 m0, s62, s78
	s_mov_b64 s[62:63], -1
	global_load_lds_dwordx4 v[146:147], off
	v_add_u32_e32 v146, s28, v149
	v_ashrrev_i32_e32 v147, 31, v146
	v_lshlrev_b64 v[146:147], 16, v[146:147]
	v_lshl_add_u64 v[146:147], s[54:55], 0, v[146:147]
	v_lshl_add_u64 v[146:147], v[146:147], 0, v[0:1]
